# decode attention Q.K: coalesced K loads (4 keys x 16 dim-chunks per load) + DPP 16-lane reduction, scores returned via LDS
# baseline (speedup 1.0000x reference)
.LBB0_306:
	s_lshl_b32 s22, s22, 10
	s_add_i32 s23, s22, 0
	s_add_i32 s23, s23, 0x20000
	s_ashr_i32 s9, s8, 31
	s_lshl_b64 s[16:17], s[16:17], 2
	v_lshl_add_u32 v22, v194, 2, s23
	s_add_u32 s16, s84, s16
	ds_write_b32 v22, v2
	s_nop 0
	s_addc_u32 s17, s85, s17
	s_waitcnt lgkmcnt(0)
	v_and_b32_e32 v148, 15, v194
	v_lshlrev_b32_e32 v150, 4, v148
	v_add_u32_e32 v151, s23, v150
	ds_read_b128 v[24:27], v151
	v_lshl_add_u32 v150, v195, 9, v150
	s_lshl_b32 s32, s20, 2
	v_lshl_add_u32 v149, v195, 2, v151
	v_add_u32_e32 v150, s32, v150
	s_lshl_b32 s32, s21, 2
	v_mov_b32_e32 v152, s32
	s_nop 3
	global_load_dword v29, v152, s[10:11]
	s_lshl_b64 s[14:15], s[14:15], 16
	v_mov_b32_e32 v146, 0
	v_mov_b32_e32 v147, 0
	global_load_dwordx4 v[78:81], v150, s[16:17]
	global_load_dwordx4 v[82:85], v150, s[16:17] offset:2048
	s_add_u32 s16, s16, 0x1000
	s_addc_u32 s17, s17, 0
	global_load_dwordx4 v[86:89], v150, s[16:17]
	global_load_dwordx4 v[90:93], v150, s[16:17] offset:2048
	s_add_u32 s16, s16, 0x1000
	s_addc_u32 s17, s17, 0
	global_load_dwordx4 v[94:97], v150, s[16:17]
	global_load_dwordx4 v[98:101], v150, s[16:17] offset:2048
	s_add_u32 s16, s16, 0x1000
	s_addc_u32 s17, s17, 0
	global_load_dwordx4 v[102:105], v150, s[16:17]
	global_load_dwordx4 v[106:109], v150, s[16:17] offset:2048
	s_add_u32 s16, s16, 0x1000
	s_addc_u32 s17, s17, 0
	global_load_dwordx4 v[110:113], v150, s[16:17]
	global_load_dwordx4 v[114:117], v150, s[16:17] offset:2048
	s_add_u32 s16, s16, 0x1000
	s_addc_u32 s17, s17, 0
	global_load_dwordx4 v[118:121], v150, s[16:17]
	global_load_dwordx4 v[122:125], v150, s[16:17] offset:2048
	s_add_u32 s16, s16, 0x1000
	s_addc_u32 s17, s17, 0
	global_load_dwordx4 v[126:129], v150, s[16:17]
	global_load_dwordx4 v[130:133], v150, s[16:17] offset:2048
	s_add_u32 s16, s16, 0x1000
	s_addc_u32 s17, s17, 0
	global_load_dwordx4 v[134:137], v150, s[16:17]
	global_load_dwordx4 v[138:141], v150, s[16:17] offset:2048
	s_add_u32 s16, s16, 0x1000
	s_addc_u32 s17, s17, 0
	s_waitcnt lgkmcnt(0)
	s_waitcnt vmcnt(15)
	v_mul_f32_e32 v142, v24, v78
	v_fmac_f32_e32 v142, v25, v79
	v_fmac_f32_e32 v142, v26, v80
	v_fmac_f32_e32 v142, v27, v81
	global_load_dwordx4 v[78:81], v150, s[16:17]
	s_waitcnt vmcnt(15)
	v_mul_f32_e32 v143, v24, v82
	v_fmac_f32_e32 v143, v25, v83
	v_fmac_f32_e32 v143, v26, v84
	v_fmac_f32_e32 v143, v27, v85
	global_load_dwordx4 v[82:85], v150, s[16:17] offset:2048
	s_add_u32 s16, s16, 0x1000
	s_addc_u32 s17, s17, 0
	s_waitcnt vmcnt(15)
	v_mul_f32_e32 v144, v24, v86
	v_fmac_f32_e32 v144, v25, v87
	v_fmac_f32_e32 v144, v26, v88
	v_fmac_f32_e32 v144, v27, v89
	global_load_dwordx4 v[86:89], v150, s[16:17]
	s_waitcnt vmcnt(15)
	v_mul_f32_e32 v145, v24, v90
	v_fmac_f32_e32 v145, v25, v91
	v_fmac_f32_e32 v145, v26, v92
	v_fmac_f32_e32 v145, v27, v93
	global_load_dwordx4 v[90:93], v150, s[16:17] offset:2048
	s_add_u32 s16, s16, 0x1000
	s_addc_u32 s17, s17, 0
	v_add_f32_dpp v142, v142, v142 quad_perm:[1,0,3,2] row_mask:0xf bank_mask:0xf
	v_add_f32_dpp v143, v143, v143 quad_perm:[1,0,3,2] row_mask:0xf bank_mask:0xf
	v_add_f32_dpp v144, v144, v144 quad_perm:[1,0,3,2] row_mask:0xf bank_mask:0xf
	v_add_f32_dpp v145, v145, v145 quad_perm:[1,0,3,2] row_mask:0xf bank_mask:0xf
	v_add_f32_dpp v142, v142, v142 quad_perm:[2,3,0,1] row_mask:0xf bank_mask:0xf
	v_add_f32_dpp v143, v143, v143 quad_perm:[2,3,0,1] row_mask:0xf bank_mask:0xf
	v_add_f32_dpp v144, v144, v144 quad_perm:[2,3,0,1] row_mask:0xf bank_mask:0xf
	v_add_f32_dpp v145, v145, v145 quad_perm:[2,3,0,1] row_mask:0xf bank_mask:0xf
	v_add_f32_dpp v142, v142, v142 row_half_mirror row_mask:0xf bank_mask:0xf
	v_add_f32_dpp v143, v143, v143 row_half_mirror row_mask:0xf bank_mask:0xf
	v_add_f32_dpp v144, v144, v144 row_half_mirror row_mask:0xf bank_mask:0xf
	v_add_f32_dpp v145, v145, v145 row_half_mirror row_mask:0xf bank_mask:0xf
	v_add_f32_dpp v142, v142, v142 row_mirror row_mask:0xf bank_mask:0xf
	v_add_f32_dpp v143, v143, v143 row_mirror row_mask:0xf bank_mask:0xf
	v_add_f32_dpp v144, v144, v144 row_mirror row_mask:0xf bank_mask:0xf
	v_add_f32_dpp v145, v145, v145 row_mirror row_mask:0xf bank_mask:0xf
	s_nop 1
	v_cmp_eq_u32_e32 vcc, 0, v148
	v_cndmask_b32_e32 v146, v146, v142, vcc
	v_cmp_eq_u32_e32 vcc, 1, v148
	v_cndmask_b32_e32 v146, v146, v143, vcc
	v_cmp_eq_u32_e32 vcc, 2, v148
	v_cndmask_b32_e32 v146, v146, v144, vcc
	v_cmp_eq_u32_e32 vcc, 3, v148
	v_cndmask_b32_e32 v146, v146, v145, vcc
	s_waitcnt vmcnt(15)
	v_mul_f32_e32 v142, v24, v94
	v_fmac_f32_e32 v142, v25, v95
	v_fmac_f32_e32 v142, v26, v96
	v_fmac_f32_e32 v142, v27, v97
	global_load_dwordx4 v[94:97], v150, s[16:17]
	s_waitcnt vmcnt(15)
	v_mul_f32_e32 v143, v24, v98
	v_fmac_f32_e32 v143, v25, v99
	v_fmac_f32_e32 v143, v26, v100
	v_fmac_f32_e32 v143, v27, v101
	global_load_dwordx4 v[98:101], v150, s[16:17] offset:2048
	s_add_u32 s16, s16, 0x1000
	s_addc_u32 s17, s17, 0
	s_waitcnt vmcnt(15)
	v_mul_f32_e32 v144, v24, v102
	v_fmac_f32_e32 v144, v25, v103
	v_fmac_f32_e32 v144, v26, v104
	v_fmac_f32_e32 v144, v27, v105
	global_load_dwordx4 v[102:105], v150, s[16:17]
	s_waitcnt vmcnt(15)
	v_mul_f32_e32 v145, v24, v106
	v_fmac_f32_e32 v145, v25, v107
	v_fmac_f32_e32 v145, v26, v108
	v_fmac_f32_e32 v145, v27, v109
	global_load_dwordx4 v[106:109], v150, s[16:17] offset:2048
	s_add_u32 s16, s16, 0x1000
	s_addc_u32 s17, s17, 0
	v_add_f32_dpp v142, v142, v142 quad_perm:[1,0,3,2] row_mask:0xf bank_mask:0xf
	v_add_f32_dpp v143, v143, v143 quad_perm:[1,0,3,2] row_mask:0xf bank_mask:0xf
	v_add_f32_dpp v144, v144, v144 quad_perm:[1,0,3,2] row_mask:0xf bank_mask:0xf
	v_add_f32_dpp v145, v145, v145 quad_perm:[1,0,3,2] row_mask:0xf bank_mask:0xf
	v_add_f32_dpp v142, v142, v142 quad_perm:[2,3,0,1] row_mask:0xf bank_mask:0xf
	v_add_f32_dpp v143, v143, v143 quad_perm:[2,3,0,1] row_mask:0xf bank_mask:0xf
	v_add_f32_dpp v144, v144, v144 quad_perm:[2,3,0,1] row_mask:0xf bank_mask:0xf
	v_add_f32_dpp v145, v145, v145 quad_perm:[2,3,0,1] row_mask:0xf bank_mask:0xf
	v_add_f32_dpp v142, v142, v142 row_half_mirror row_mask:0xf bank_mask:0xf
	v_add_f32_dpp v143, v143, v143 row_half_mirror row_mask:0xf bank_mask:0xf
	v_add_f32_dpp v144, v144, v144 row_half_mirror row_mask:0xf bank_mask:0xf
	v_add_f32_dpp v145, v145, v145 row_half_mirror row_mask:0xf bank_mask:0xf
	v_add_f32_dpp v142, v142, v142 row_mirror row_mask:0xf bank_mask:0xf
	v_add_f32_dpp v143, v143, v143 row_mirror row_mask:0xf bank_mask:0xf
	v_add_f32_dpp v144, v144, v144 row_mirror row_mask:0xf bank_mask:0xf
	v_add_f32_dpp v145, v145, v145 row_mirror row_mask:0xf bank_mask:0xf
	s_nop 1
	v_cmp_eq_u32_e32 vcc, 4, v148
	v_cndmask_b32_e32 v146, v146, v142, vcc
	v_cmp_eq_u32_e32 vcc, 5, v148
	v_cndmask_b32_e32 v146, v146, v143, vcc
	v_cmp_eq_u32_e32 vcc, 6, v148
	v_cndmask_b32_e32 v146, v146, v144, vcc
	v_cmp_eq_u32_e32 vcc, 7, v148
	v_cndmask_b32_e32 v146, v146, v145, vcc
	s_waitcnt vmcnt(15)
	v_mul_f32_e32 v142, v24, v110
	v_fmac_f32_e32 v142, v25, v111
	v_fmac_f32_e32 v142, v26, v112
	v_fmac_f32_e32 v142, v27, v113
	global_load_dwordx4 v[110:113], v150, s[16:17]
	s_waitcnt vmcnt(15)
	v_mul_f32_e32 v143, v24, v114
	v_fmac_f32_e32 v143, v25, v115
	v_fmac_f32_e32 v143, v26, v116
	v_fmac_f32_e32 v143, v27, v117
	global_load_dwordx4 v[114:117], v150, s[16:17] offset:2048
	s_add_u32 s16, s16, 0x1000
	s_addc_u32 s17, s17, 0
	s_waitcnt vmcnt(15)
	v_mul_f32_e32 v144, v24, v118
	v_fmac_f32_e32 v144, v25, v119
	v_fmac_f32_e32 v144, v26, v120
	v_fmac_f32_e32 v144, v27, v121
	global_load_dwordx4 v[118:121], v150, s[16:17]
	s_waitcnt vmcnt(15)
	v_mul_f32_e32 v145, v24, v122
	v_fmac_f32_e32 v145, v25, v123
	v_fmac_f32_e32 v145, v26, v124
	v_fmac_f32_e32 v145, v27, v125
	global_load_dwordx4 v[122:125], v150, s[16:17] offset:2048
	s_add_u32 s16, s16, 0x1000
	s_addc_u32 s17, s17, 0
	v_add_f32_dpp v142, v142, v142 quad_perm:[1,0,3,2] row_mask:0xf bank_mask:0xf
	v_add_f32_dpp v143, v143, v143 quad_perm:[1,0,3,2] row_mask:0xf bank_mask:0xf
	v_add_f32_dpp v144, v144, v144 quad_perm:[1,0,3,2] row_mask:0xf bank_mask:0xf
	v_add_f32_dpp v145, v145, v145 quad_perm:[1,0,3,2] row_mask:0xf bank_mask:0xf
	v_add_f32_dpp v142, v142, v142 quad_perm:[2,3,0,1] row_mask:0xf bank_mask:0xf
	v_add_f32_dpp v143, v143, v143 quad_perm:[2,3,0,1] row_mask:0xf bank_mask:0xf
	v_add_f32_dpp v144, v144, v144 quad_perm:[2,3,0,1] row_mask:0xf bank_mask:0xf
	v_add_f32_dpp v145, v145, v145 quad_perm:[2,3,0,1] row_mask:0xf bank_mask:0xf
	v_add_f32_dpp v142, v142, v142 row_half_mirror row_mask:0xf bank_mask:0xf
	v_add_f32_dpp v143, v143, v143 row_half_mirror row_mask:0xf bank_mask:0xf
	v_add_f32_dpp v144, v144, v144 row_half_mirror row_mask:0xf bank_mask:0xf
	v_add_f32_dpp v145, v145, v145 row_half_mirror row_mask:0xf bank_mask:0xf
	v_add_f32_dpp v142, v142, v142 row_mirror row_mask:0xf bank_mask:0xf
	v_add_f32_dpp v143, v143, v143 row_mirror row_mask:0xf bank_mask:0xf
	v_add_f32_dpp v144, v144, v144 row_mirror row_mask:0xf bank_mask:0xf
	v_add_f32_dpp v145, v145, v145 row_mirror row_mask:0xf bank_mask:0xf
	s_nop 1
	v_cmp_eq_u32_e32 vcc, 8, v148
	v_cndmask_b32_e32 v146, v146, v142, vcc
	v_cmp_eq_u32_e32 vcc, 9, v148
	v_cndmask_b32_e32 v146, v146, v143, vcc
	v_cmp_eq_u32_e32 vcc, 10, v148
	v_cndmask_b32_e32 v146, v146, v144, vcc
	v_cmp_eq_u32_e32 vcc, 11, v148
	v_cndmask_b32_e32 v146, v146, v145, vcc
	s_waitcnt vmcnt(15)
	v_mul_f32_e32 v142, v24, v126
	v_fmac_f32_e32 v142, v25, v127
	v_fmac_f32_e32 v142, v26, v128
	v_fmac_f32_e32 v142, v27, v129
	global_load_dwordx4 v[126:129], v150, s[16:17]
	s_waitcnt vmcnt(15)
	v_mul_f32_e32 v143, v24, v130
	v_fmac_f32_e32 v143, v25, v131
	v_fmac_f32_e32 v143, v26, v132
	v_fmac_f32_e32 v143, v27, v133
	global_load_dwordx4 v[130:133], v150, s[16:17] offset:2048
	s_add_u32 s16, s16, 0x1000
	s_addc_u32 s17, s17, 0
	s_waitcnt vmcnt(15)
	v_mul_f32_e32 v144, v24, v134
	v_fmac_f32_e32 v144, v25, v135
	v_fmac_f32_e32 v144, v26, v136
	v_fmac_f32_e32 v144, v27, v137
	global_load_dwordx4 v[134:137], v150, s[16:17]
	s_waitcnt vmcnt(15)
	v_mul_f32_e32 v145, v24, v138
	v_fmac_f32_e32 v145, v25, v139
	v_fmac_f32_e32 v145, v26, v140
	v_fmac_f32_e32 v145, v27, v141
	global_load_dwordx4 v[138:141], v150, s[16:17] offset:2048
	s_add_u32 s16, s16, 0x1000
	s_addc_u32 s17, s17, 0
	v_add_f32_dpp v142, v142, v142 quad_perm:[1,0,3,2] row_mask:0xf bank_mask:0xf
	v_add_f32_dpp v143, v143, v143 quad_perm:[1,0,3,2] row_mask:0xf bank_mask:0xf
	v_add_f32_dpp v144, v144, v144 quad_perm:[1,0,3,2] row_mask:0xf bank_mask:0xf
	v_add_f32_dpp v145, v145, v145 quad_perm:[1,0,3,2] row_mask:0xf bank_mask:0xf
	v_add_f32_dpp v142, v142, v142 quad_perm:[2,3,0,1] row_mask:0xf bank_mask:0xf
	v_add_f32_dpp v143, v143, v143 quad_perm:[2,3,0,1] row_mask:0xf bank_mask:0xf
	v_add_f32_dpp v144, v144, v144 quad_perm:[2,3,0,1] row_mask:0xf bank_mask:0xf
	v_add_f32_dpp v145, v145, v145 quad_perm:[2,3,0,1] row_mask:0xf bank_mask:0xf
	v_add_f32_dpp v142, v142, v142 row_half_mirror row_mask:0xf bank_mask:0xf
	v_add_f32_dpp v143, v143, v143 row_half_mirror row_mask:0xf bank_mask:0xf
	v_add_f32_dpp v144, v144, v144 row_half_mirror row_mask:0xf bank_mask:0xf
	v_add_f32_dpp v145, v145, v145 row_half_mirror row_mask:0xf bank_mask:0xf
	v_add_f32_dpp v142, v142, v142 row_mirror row_mask:0xf bank_mask:0xf
	v_add_f32_dpp v143, v143, v143 row_mirror row_mask:0xf bank_mask:0xf
	v_add_f32_dpp v144, v144, v144 row_mirror row_mask:0xf bank_mask:0xf
	v_add_f32_dpp v145, v145, v145 row_mirror row_mask:0xf bank_mask:0xf
	s_nop 1
	v_cmp_eq_u32_e32 vcc, 12, v148
	v_cndmask_b32_e32 v146, v146, v142, vcc
	v_cmp_eq_u32_e32 vcc, 13, v148
	v_cndmask_b32_e32 v146, v146, v143, vcc
	v_cmp_eq_u32_e32 vcc, 14, v148
	v_cndmask_b32_e32 v146, v146, v144, vcc
	v_cmp_eq_u32_e32 vcc, 15, v148
	v_cndmask_b32_e32 v146, v146, v145, vcc
	s_waitcnt vmcnt(15)
	v_mul_f32_e32 v142, v24, v78
	v_fmac_f32_e32 v142, v25, v79
	v_fmac_f32_e32 v142, v26, v80
	v_fmac_f32_e32 v142, v27, v81
	s_waitcnt vmcnt(14)
	v_mul_f32_e32 v143, v24, v82
	v_fmac_f32_e32 v143, v25, v83
	v_fmac_f32_e32 v143, v26, v84
	v_fmac_f32_e32 v143, v27, v85
	s_waitcnt vmcnt(13)
	v_mul_f32_e32 v144, v24, v86
	v_fmac_f32_e32 v144, v25, v87
	v_fmac_f32_e32 v144, v26, v88
	v_fmac_f32_e32 v144, v27, v89
	s_waitcnt vmcnt(12)
	v_mul_f32_e32 v145, v24, v90
	v_fmac_f32_e32 v145, v25, v91
	v_fmac_f32_e32 v145, v26, v92
	v_fmac_f32_e32 v145, v27, v93
	v_add_f32_dpp v142, v142, v142 quad_perm:[1,0,3,2] row_mask:0xf bank_mask:0xf
	v_add_f32_dpp v143, v143, v143 quad_perm:[1,0,3,2] row_mask:0xf bank_mask:0xf
	v_add_f32_dpp v144, v144, v144 quad_perm:[1,0,3,2] row_mask:0xf bank_mask:0xf
	v_add_f32_dpp v145, v145, v145 quad_perm:[1,0,3,2] row_mask:0xf bank_mask:0xf
	v_add_f32_dpp v142, v142, v142 quad_perm:[2,3,0,1] row_mask:0xf bank_mask:0xf
	v_add_f32_dpp v143, v143, v143 quad_perm:[2,3,0,1] row_mask:0xf bank_mask:0xf
	v_add_f32_dpp v144, v144, v144 quad_perm:[2,3,0,1] row_mask:0xf bank_mask:0xf
	v_add_f32_dpp v145, v145, v145 quad_perm:[2,3,0,1] row_mask:0xf bank_mask:0xf
	v_add_f32_dpp v142, v142, v142 row_half_mirror row_mask:0xf bank_mask:0xf
	v_add_f32_dpp v143, v143, v143 row_half_mirror row_mask:0xf bank_mask:0xf
	v_add_f32_dpp v144, v144, v144 row_half_mirror row_mask:0xf bank_mask:0xf
	v_add_f32_dpp v145, v145, v145 row_half_mirror row_mask:0xf bank_mask:0xf
	v_add_f32_dpp v142, v142, v142 row_mirror row_mask:0xf bank_mask:0xf
	v_add_f32_dpp v143, v143, v143 row_mirror row_mask:0xf bank_mask:0xf
	v_add_f32_dpp v144, v144, v144 row_mirror row_mask:0xf bank_mask:0xf
	v_add_f32_dpp v145, v145, v145 row_mirror row_mask:0xf bank_mask:0xf
	s_nop 1
	v_cmp_eq_u32_e32 vcc, 0, v148
	v_cndmask_b32_e32 v147, v147, v142, vcc
	v_cmp_eq_u32_e32 vcc, 1, v148
	v_cndmask_b32_e32 v147, v147, v143, vcc
	v_cmp_eq_u32_e32 vcc, 2, v148
	v_cndmask_b32_e32 v147, v147, v144, vcc
	v_cmp_eq_u32_e32 vcc, 3, v148
	v_cndmask_b32_e32 v147, v147, v145, vcc
	s_waitcnt vmcnt(11)
	v_mul_f32_e32 v142, v24, v94
	v_fmac_f32_e32 v142, v25, v95
	v_fmac_f32_e32 v142, v26, v96
	v_fmac_f32_e32 v142, v27, v97
	s_waitcnt vmcnt(10)
	v_mul_f32_e32 v143, v24, v98
	v_fmac_f32_e32 v143, v25, v99
	v_fmac_f32_e32 v143, v26, v100
	v_fmac_f32_e32 v143, v27, v101
	s_waitcnt vmcnt(9)
	v_mul_f32_e32 v144, v24, v102
	v_fmac_f32_e32 v144, v25, v103
	v_fmac_f32_e32 v144, v26, v104
	v_fmac_f32_e32 v144, v27, v105
	s_waitcnt vmcnt(8)
	v_mul_f32_e32 v145, v24, v106
	v_fmac_f32_e32 v145, v25, v107
	v_fmac_f32_e32 v145, v26, v108
	v_fmac_f32_e32 v145, v27, v109
	v_add_f32_dpp v142, v142, v142 quad_perm:[1,0,3,2] row_mask:0xf bank_mask:0xf
	v_add_f32_dpp v143, v143, v143 quad_perm:[1,0,3,2] row_mask:0xf bank_mask:0xf
	v_add_f32_dpp v144, v144, v144 quad_perm:[1,0,3,2] row_mask:0xf bank_mask:0xf
	v_add_f32_dpp v145, v145, v145 quad_perm:[1,0,3,2] row_mask:0xf bank_mask:0xf
	v_add_f32_dpp v142, v142, v142 quad_perm:[2,3,0,1] row_mask:0xf bank_mask:0xf
	v_add_f32_dpp v143, v143, v143 quad_perm:[2,3,0,1] row_mask:0xf bank_mask:0xf
	v_add_f32_dpp v144, v144, v144 quad_perm:[2,3,0,1] row_mask:0xf bank_mask:0xf
	v_add_f32_dpp v145, v145, v145 quad_perm:[2,3,0,1] row_mask:0xf bank_mask:0xf
	v_add_f32_dpp v142, v142, v142 row_half_mirror row_mask:0xf bank_mask:0xf
	v_add_f32_dpp v143, v143, v143 row_half_mirror row_mask:0xf bank_mask:0xf
	v_add_f32_dpp v144, v144, v144 row_half_mirror row_mask:0xf bank_mask:0xf
	v_add_f32_dpp v145, v145, v145 row_half_mirror row_mask:0xf bank_mask:0xf
	v_add_f32_dpp v142, v142, v142 row_mirror row_mask:0xf bank_mask:0xf
	v_add_f32_dpp v143, v143, v143 row_mirror row_mask:0xf bank_mask:0xf
	v_add_f32_dpp v144, v144, v144 row_mirror row_mask:0xf bank_mask:0xf
	v_add_f32_dpp v145, v145, v145 row_mirror row_mask:0xf bank_mask:0xf
	s_nop 1
	v_cmp_eq_u32_e32 vcc, 4, v148
	v_cndmask_b32_e32 v147, v147, v142, vcc
	v_cmp_eq_u32_e32 vcc, 5, v148
	v_cndmask_b32_e32 v147, v147, v143, vcc
	v_cmp_eq_u32_e32 vcc, 6, v148
	v_cndmask_b32_e32 v147, v147, v144, vcc
	v_cmp_eq_u32_e32 vcc, 7, v148
	v_cndmask_b32_e32 v147, v147, v145, vcc
	s_waitcnt vmcnt(7)
	v_mul_f32_e32 v142, v24, v110
	v_fmac_f32_e32 v142, v25, v111
	v_fmac_f32_e32 v142, v26, v112
	v_fmac_f32_e32 v142, v27, v113
	s_waitcnt vmcnt(6)
	v_mul_f32_e32 v143, v24, v114
	v_fmac_f32_e32 v143, v25, v115
	v_fmac_f32_e32 v143, v26, v116
	v_fmac_f32_e32 v143, v27, v117
	s_waitcnt vmcnt(5)
	v_mul_f32_e32 v144, v24, v118
	v_fmac_f32_e32 v144, v25, v119
	v_fmac_f32_e32 v144, v26, v120
	v_fmac_f32_e32 v144, v27, v121
	s_waitcnt vmcnt(4)
	v_mul_f32_e32 v145, v24, v122
	v_fmac_f32_e32 v145, v25, v123
	v_fmac_f32_e32 v145, v26, v124
	v_fmac_f32_e32 v145, v27, v125
	v_add_f32_dpp v142, v142, v142 quad_perm:[1,0,3,2] row_mask:0xf bank_mask:0xf
	v_add_f32_dpp v143, v143, v143 quad_perm:[1,0,3,2] row_mask:0xf bank_mask:0xf
	v_add_f32_dpp v144, v144, v144 quad_perm:[1,0,3,2] row_mask:0xf bank_mask:0xf
	v_add_f32_dpp v145, v145, v145 quad_perm:[1,0,3,2] row_mask:0xf bank_mask:0xf
	v_add_f32_dpp v142, v142, v142 quad_perm:[2,3,0,1] row_mask:0xf bank_mask:0xf
	v_add_f32_dpp v143, v143, v143 quad_perm:[2,3,0,1] row_mask:0xf bank_mask:0xf
	v_add_f32_dpp v144, v144, v144 quad_perm:[2,3,0,1] row_mask:0xf bank_mask:0xf
	v_add_f32_dpp v145, v145, v145 quad_perm:[2,3,0,1] row_mask:0xf bank_mask:0xf
	v_add_f32_dpp v142, v142, v142 row_half_mirror row_mask:0xf bank_mask:0xf
	v_add_f32_dpp v143, v143, v143 row_half_mirror row_mask:0xf bank_mask:0xf
	v_add_f32_dpp v144, v144, v144 row_half_mirror row_mask:0xf bank_mask:0xf
	v_add_f32_dpp v145, v145, v145 row_half_mirror row_mask:0xf bank_mask:0xf
	v_add_f32_dpp v142, v142, v142 row_mirror row_mask:0xf bank_mask:0xf
	v_add_f32_dpp v143, v143, v143 row_mirror row_mask:0xf bank_mask:0xf
	v_add_f32_dpp v144, v144, v144 row_mirror row_mask:0xf bank_mask:0xf
	v_add_f32_dpp v145, v145, v145 row_mirror row_mask:0xf bank_mask:0xf
	s_nop 1
	v_cmp_eq_u32_e32 vcc, 8, v148
	v_cndmask_b32_e32 v147, v147, v142, vcc
	v_cmp_eq_u32_e32 vcc, 9, v148
	v_cndmask_b32_e32 v147, v147, v143, vcc
	v_cmp_eq_u32_e32 vcc, 10, v148
	v_cndmask_b32_e32 v147, v147, v144, vcc
	v_cmp_eq_u32_e32 vcc, 11, v148
	v_cndmask_b32_e32 v147, v147, v145, vcc
	s_waitcnt vmcnt(3)
	v_mul_f32_e32 v142, v24, v126
	v_fmac_f32_e32 v142, v25, v127
	v_fmac_f32_e32 v142, v26, v128
	v_fmac_f32_e32 v142, v27, v129
	s_waitcnt vmcnt(2)
	v_mul_f32_e32 v143, v24, v130
	v_fmac_f32_e32 v143, v25, v131
	v_fmac_f32_e32 v143, v26, v132
	v_fmac_f32_e32 v143, v27, v133
	s_waitcnt vmcnt(1)
	v_mul_f32_e32 v144, v24, v134
	v_fmac_f32_e32 v144, v25, v135
	v_fmac_f32_e32 v144, v26, v136
	v_fmac_f32_e32 v144, v27, v137
	s_waitcnt vmcnt(0)
	v_mul_f32_e32 v145, v24, v138
	v_fmac_f32_e32 v145, v25, v139
	v_fmac_f32_e32 v145, v26, v140
	v_fmac_f32_e32 v145, v27, v141
	v_add_f32_dpp v142, v142, v142 quad_perm:[1,0,3,2] row_mask:0xf bank_mask:0xf
	v_add_f32_dpp v143, v143, v143 quad_perm:[1,0,3,2] row_mask:0xf bank_mask:0xf
	v_add_f32_dpp v144, v144, v144 quad_perm:[1,0,3,2] row_mask:0xf bank_mask:0xf
	v_add_f32_dpp v145, v145, v145 quad_perm:[1,0,3,2] row_mask:0xf bank_mask:0xf
	v_add_f32_dpp v142, v142, v142 quad_perm:[2,3,0,1] row_mask:0xf bank_mask:0xf
	v_add_f32_dpp v143, v143, v143 quad_perm:[2,3,0,1] row_mask:0xf bank_mask:0xf
	v_add_f32_dpp v144, v144, v144 quad_perm:[2,3,0,1] row_mask:0xf bank_mask:0xf
	v_add_f32_dpp v145, v145, v145 quad_perm:[2,3,0,1] row_mask:0xf bank_mask:0xf
	v_add_f32_dpp v142, v142, v142 row_half_mirror row_mask:0xf bank_mask:0xf
	v_add_f32_dpp v143, v143, v143 row_half_mirror row_mask:0xf bank_mask:0xf
	v_add_f32_dpp v144, v144, v144 row_half_mirror row_mask:0xf bank_mask:0xf
	v_add_f32_dpp v145, v145, v145 row_half_mirror row_mask:0xf bank_mask:0xf
	v_add_f32_dpp v142, v142, v142 row_mirror row_mask:0xf bank_mask:0xf
	v_add_f32_dpp v143, v143, v143 row_mirror row_mask:0xf bank_mask:0xf
	v_add_f32_dpp v144, v144, v144 row_mirror row_mask:0xf bank_mask:0xf
	v_add_f32_dpp v145, v145, v145 row_mirror row_mask:0xf bank_mask:0xf
	s_nop 1
	v_cmp_eq_u32_e32 vcc, 12, v148
	v_cndmask_b32_e32 v147, v147, v142, vcc
	v_cmp_eq_u32_e32 vcc, 13, v148
	v_cndmask_b32_e32 v147, v147, v143, vcc
	v_cmp_eq_u32_e32 vcc, 14, v148
	v_cndmask_b32_e32 v147, v147, v144, vcc
	v_cmp_eq_u32_e32 vcc, 15, v148
	v_cndmask_b32_e32 v147, v147, v145, vcc
	ds_write_b32 v149, v146 offset:256
	ds_write_b32 v149, v147 offset:512
	s_waitcnt lgkmcnt(0)
	ds_read_b32 v23, v22 offset:256
	ds_read_b32 v2, v22 offset:512
	s_waitcnt lgkmcnt(0)
	v_max_f32_e32 v3, v23, v2
	ds_bpermute_b32 v4, v16, v3
	v_add_f32_e32 v77, v20, v21
	v_mov_b32_e32 v45, s15
	v_add_u32_e32 v82, s22, v65
	s_waitcnt lgkmcnt(0)
	v_max_f32_e32 v4, v4, v4
	v_max_f32_e32 v3, v3, v4
	ds_bpermute_b32 v4, v17, v3
	s_waitcnt lgkmcnt(0)
	v_max_f32_e32 v4, v4, v4
	v_max_f32_e32 v3, v3, v4
	ds_bpermute_b32 v4, v18, v3
	s_waitcnt lgkmcnt(0)
	v_max_f32_e32 v4, v4, v4
	v_max_f32_e32 v3, v3, v4
	ds_bpermute_b32 v4, v19, v3
	s_waitcnt lgkmcnt(0)
	v_max_f32_e32 v4, v4, v4
	v_max_f32_e32 v3, v3, v4
	ds_bpermute_b32 v4, v76, v3
	s_waitcnt lgkmcnt(0)
	v_max_f32_e32 v4, v4, v4
	v_max_f32_e32 v3, v3, v4
	ds_bpermute_b32 v4, v75, v3
	s_waitcnt vmcnt(0)
	v_mul_f32_e32 v78, 0x3fb8aa3b, v29
	s_waitcnt lgkmcnt(0)
	v_max_f32_e32 v4, v4, v4
	v_max_f32_e32 v3, v3, v4
	v_max3_f32 v79, v3, v77, v78
	v_sub_f32_e32 v3, v23, v79
	v_sub_f32_e32 v2, v2, v79
	v_exp_f32_e32 v3, v3
	v_exp_f32_e32 v2, v2
	ds_write2st64_b32 v22, v3, v2 offset0:1 offset1:2
	v_add_f32_e32 v4, v3, v2
	ds_bpermute_b32 v5, v16, v4
	v_cndmask_b32_e64 v16, 0, 1, s[4:5]
	v_lshlrev_b32_e32 v16, 6, v16
	v_add_u32_e32 v20, v50, v16
	v_lshl_or_b32 v44, v20, 2, s14
	s_waitcnt lgkmcnt(0)
	v_add_f32_e32 v4, v4, v5
	ds_bpermute_b32 v5, v17, v4
	v_add_u32_e32 v17, v51, v16
	v_add_u32_e32 v21, v52, v16
	v_lshl_add_u64 v[2:3], v[14:15], 0, v[44:45]
	v_lshl_or_b32 v44, v17, 2, s14
	s_waitcnt lgkmcnt(0)
	v_add_f32_e32 v4, v4, v5
	ds_bpermute_b32 v5, v18, v4
	v_add_u32_e32 v23, v53, v16
	v_add_u32_e32 v24, v54, v16
	v_add_u32_e32 v25, v55, v16
	v_add_u32_e32 v26, v56, v16
	s_waitcnt lgkmcnt(0)
	v_add_f32_e32 v4, v4, v5
	ds_bpermute_b32 v5, v19, v4
	v_add_u32_e32 v28, v57, v16
	v_add_u32_e32 v30, v58, v16
	v_add_u32_e32 v19, v59, v16
	v_add_u32_e32 v34, v60, v16
	s_waitcnt lgkmcnt(0)
	v_add_f32_e32 v4, v4, v5
	ds_bpermute_b32 v5, v76, v4
	v_add_u32_e32 v36, v61, v16
	v_add_u32_e32 v38, v62, v16
	v_add_u32_e32 v40, v63, v16
	v_add_u32_e32 v42, v64, v16
	s_waitcnt lgkmcnt(0)
	v_add_f32_e32 v80, v4, v5
	v_lshl_add_u64 v[4:5], v[14:15], 0, v[44:45]
	v_lshl_or_b32 v44, v21, 2, s14
	v_add_u32_e32 v46, v49, v16
	v_lshl_add_u64 v[16:17], v[14:15], 0, v[44:45]
	v_lshl_or_b32 v44, v23, 2, s14
	v_lshl_add_u64 v[20:21], v[14:15], 0, v[44:45]
	v_lshl_or_b32 v44, v24, 2, s14
	v_lshl_add_u64 v[22:23], v[14:15], 0, v[44:45]
	v_lshl_or_b32 v44, v25, 2, s14
	v_lshl_add_u64 v[24:25], v[14:15], 0, v[44:45]
	v_lshl_or_b32 v44, v26, 2, s14
	v_lshl_add_u64 v[26:27], v[14:15], 0, v[44:45]
	v_lshl_or_b32 v44, v28, 2, s14
	v_lshl_add_u64 v[28:29], v[14:15], 0, v[44:45]
	v_lshl_or_b32 v44, v30, 2, s14
	v_lshl_add_u64 v[30:31], v[14:15], 0, v[44:45]
	v_lshl_or_b32 v44, v19, 2, s14
	v_lshl_add_u64 v[32:33], v[14:15], 0, v[44:45]
	v_lshl_or_b32 v44, v34, 2, s14
	v_lshl_add_u64 v[34:35], v[14:15], 0, v[44:45]
	v_lshl_or_b32 v44, v36, 2, s14
	ds_bpermute_b32 v81, v75, v80
	v_lshl_add_u64 v[36:37], v[14:15], 0, v[44:45]
	v_lshl_or_b32 v44, v38, 2, s14
	v_lshl_add_u64 v[38:39], v[14:15], 0, v[44:45]
	v_lshl_or_b32 v44, v40, 2, s14
	s_waitcnt lgkmcnt(0)
	v_lshl_add_u64 v[40:41], v[14:15], 0, v[44:45]
	v_lshl_or_b32 v44, v42, 2, s14
	v_mov_b32_e32 v18, 0
	v_lshl_add_u64 v[42:43], v[14:15], 0, v[44:45]
	v_lshl_or_b32 v44, v46, 2, s14
	v_lshl_add_u64 v[44:45], v[14:15], 0, v[44:45]
	s_mov_b64 s[14:15], 0
	v_mov_b32_e32 v19, v18
	v_mov_b32_e32 v46, v18
	v_mov_b32_e32 v47, v18
